# v79 + attention items run without the younger-half priority raise (all waves priority 0)
# baseline (speedup 1.0000x reference)
.Lprio_young:
	s_setprio 0
